# 9 fixes: + GLA chain partial-sum LDS reads batched (5 in flight)
# speedup vs baseline: 1.0036x; 1.0036x over previous
.LBB0_893:
	v_lshl_add_u64 v[54:55], s[16:17], 0, v[202:203]
	s_mov_b32 s22, 0x29c60000
	s_nop 2
	v_add_co_u32_e32 v42, vcc, s22, v54
	s_mov_b32 s22, 0x29c61000
	s_nop 0
	v_addc_co_u32_e32 v43, vcc, 0, v55, vcc
	global_load_dwordx4 v[106:109], v[42:43], off offset:1280
	global_load_dwordx4 v[102:105], v[42:43], off offset:2304
	global_load_dwordx4 v[98:101], v[42:43], off offset:3328
	v_add_co_u32_e32 v42, vcc, s22, v54
	s_mov_b32 s22, 0x2ac60000
	s_nop 0
	v_addc_co_u32_e32 v43, vcc, 0, v55, vcc
	v_add_co_u32_e32 v50, vcc, s22, v54
	v_lshl_add_u64 v[52:53], s[16:17], 0, v[204:205]
	s_nop 0
	v_addc_co_u32_e32 v51, vcc, 0, v55, vcc
	s_mov_b32 s22, 0x2dc58000
	v_add_co_u32_e32 v58, vcc, s22, v52
	s_mov_b32 s22, 0x2ac61000
	s_nop 0
	v_addc_co_u32_e32 v59, vcc, 0, v53, vcc
	v_add_co_u32_e32 v54, vcc, s22, v54
	v_lshl_add_u64 v[66:67], s[16:17], 0, v[206:207]
	s_nop 0
	v_addc_co_u32_e32 v55, vcc, 0, v55, vcc
	v_lshl_add_u64 v[118:119], s[16:17], 0, v[200:201]
	global_load_dwordx4 v[110:113], v[42:43], off offset:256
	s_nop 0
	global_load_dwordx4 v[42:45], v[50:51], off offset:1280
	global_load_dwordx4 v[46:49], v[50:51], off offset:2304
	global_load_dwordx4 v[70:73], v[58:59], off offset:2304
	s_nop 0
	global_load_dwordx4 v[50:53], v[50:51], off offset:3328
	s_nop 0
	global_load_dwordx4 v[54:57], v[54:55], off offset:256
	s_nop 0
	global_load_dwordx4 v[58:61], v[58:59], off offset:2368
	s_nop 0
	global_load_dwordx4 v[90:93], v[66:67], off offset:-2048
	global_load_dwordx4 v[94:97], v[66:67], off offset:-1024
	global_load_dwordx4 v[62:65], v[66:67], off
	s_nop 0
	global_load_dwordx4 v[66:69], v[66:67], off offset:1024
	v_add_u32_e32 v139, s5, v213
	global_load_dwordx4 v[118:121], v[118:119], off
	v_cvt_pk_bf16_f32 v214, v126, v127
	v_cvt_pk_bf16_f32 v215, v128, v129
	v_cvt_pk_bf16_f32 v216, v130, v131
	v_cvt_pk_bf16_f32 v217, v132, v133
	s_add_i32 s30, s29, 2
	s_waitcnt vmcnt(29)
	v_mfma_f32_16x16x32_bf16 v[234:237], v[214:217], v[74:77], 0
	s_cmp_lt_u32 s29, 30
	s_cselect_b32 s22, s30, 31
	s_add_u32 s22, s8, s22
	s_addc_u32 s23, s9, 0
	s_lshl_b64 s[54:55], s[22:23], 5
	s_nop 2
	ds_write_b128 v139, v[234:237]
	s_waitcnt vmcnt(28)
	v_mfma_f32_16x16x32_bf16 v[234:237], v[214:217], v[78:81], 0
	s_add_u32 s56, s54, s12
	s_addc_u32 s57, s55, s13
	s_or_b64 s[54:55], s[54:55], s[48:49]
	s_lshl_b64 s[56:57], s[56:57], 10
	s_lshl_b64 s[58:59], s[22:23], 10
	s_nop 2
	ds_write_b128 v139, v[234:237] offset:1024
	s_waitcnt vmcnt(27)
	v_mfma_f32_16x16x32_bf16 v[234:237], v[214:217], v[82:85], 0
	s_lshl_b64 s[66:67], s[22:23], 15
	s_lshl_b64 s[54:55], s[54:55], 11
	s_lshl_b64 s[22:23], s[22:23], 17
	s_waitcnt vmcnt(26)
	v_mfma_f32_16x16x32_bf16 v[214:217], v[214:217], v[86:89], 0
	s_cmp_gt_u32 s29, 29
	s_nop 1
	ds_write_b128 v139, v[234:237] offset:2048
	v_lshl_add_u64 v[200:201], v[200:201], 0, s[64:65]
	v_lshl_add_u64 v[206:207], v[206:207], 0, s[62:63]
	s_mov_b32 s29, s30
	s_nop 0
	ds_write_b128 v139, v[214:217] offset:3072
	v_cvt_pk_bf16_f32 v214, v122, v123
	v_cvt_pk_bf16_f32 v215, v124, v125
	v_cvt_pk_bf16_f32 v216, v134, v135
	v_cvt_pk_bf16_f32 v217, v136, v137
	s_nop 0
	v_mfma_f32_16x16x32_bf16 v[74:77], v[214:217], v[74:77], 0
	s_nop 7
	ds_write_b128 v139, v[74:77] offset:4096
	v_mfma_f32_16x16x32_bf16 v[74:77], v[214:217], v[78:81], 0
	s_nop 7
	ds_write_b128 v139, v[74:77] offset:5120
	v_mfma_f32_16x16x32_bf16 v[74:77], v[214:217], v[82:85], 0
	v_add_u32_e32 v82, s25, v213
	s_nop 6
	ds_write_b128 v139, v[74:77] offset:6144
	v_mfma_f32_16x16x32_bf16 v[74:77], v[214:217], v[86:89], 0
	s_nop 7
	ds_write_b128 v139, v[74:77] offset:7168
	s_waitcnt lgkmcnt(0)
	s_barrier
	ds_read_b128 v[74:77], v82
	ds_read_b128 v[238:241], v82 offset:8192
	ds_read_b128 v[242:245], v82 offset:16384
	ds_read_b128 v[246:249], v82 offset:24576
	ds_read_b128 v[250:253], v82 offset:32768
	v_add_u32_e32 v139, s5, v212
	s_waitcnt vmcnt(15) lgkmcnt(4)
	v_pk_add_f32 v[78:79], v[116:117], v[76:77]
	v_pk_add_f32 v[80:81], v[114:115], v[74:75]
	ds_read_b128 v[74:77], v82 offset:40960
	v_lshl_add_u64 v[114:115], v[198:199], 0, s[22:23]
	s_mov_b64 s[22:23], 0x10000
	v_lshl_add_u64 v[202:203], v[202:203], 0, s[22:23]
	s_mov_b64 s[22:23], 0x800
	s_waitcnt lgkmcnt(4)
	v_pk_add_f32 v[78:79], v[78:79], v[240:241]
	v_pk_add_f32 v[80:81], v[80:81], v[238:239]
	ds_read_b128 v[238:241], v82 offset:49152
	v_lshl_add_u64 v[204:205], v[204:205], 0, s[22:23]
	s_waitcnt lgkmcnt(4)
	v_pk_add_f32 v[78:79], v[78:79], v[244:245]
	v_pk_add_f32 v[80:81], v[80:81], v[242:243]
	ds_read_b128 v[242:245], v82 offset:57344
	s_waitcnt lgkmcnt(4)
	v_pk_add_f32 v[78:79], v[78:79], v[248:249]
	v_pk_add_f32 v[80:81], v[80:81], v[246:247]
	s_waitcnt lgkmcnt(3)
	v_pk_add_f32 v[78:79], v[78:79], v[252:253]
	v_pk_add_f32 v[80:81], v[80:81], v[250:251]
	s_waitcnt lgkmcnt(2)
	v_pk_add_f32 v[78:79], v[78:79], v[76:77]
	v_pk_add_f32 v[80:81], v[80:81], v[74:75]
	s_waitcnt lgkmcnt(1)
	v_pk_add_f32 v[78:79], v[78:79], v[240:241]
	v_pk_add_f32 v[80:81], v[80:81], v[238:239]
	s_waitcnt lgkmcnt(0)
	v_pk_add_f32 v[76:77], v[78:79], v[244:245]
	v_or_b32_e32 v79, s21, v211
	v_or_b32_e32 v78, s20, v210
	v_lshlrev_b64 v[78:79], 13, v[78:79]
	v_pk_add_f32 v[74:75], v[80:81], v[242:243]
	v_lshl_add_u64 v[78:79], v[196:197], 0, v[78:79]
	global_store_dwordx4 v[78:79], v[74:77], off
	v_lshl_add_u64 v[210:211], v[210:211], 0, s[52:53]
	s_nop 0
	v_pk_mul_f32 v[76:77], v[32:33], v[128:129]
	v_pk_mul_f32 v[74:75], v[30:31], v[126:127]
	v_pk_mul_f32 v[32:33], v[32:33], v[124:125]
	v_pk_mul_f32 v[30:31], v[30:31], v[122:123]
	v_mfma_f32_16x16x32_bf16 v[74:77], v[18:21], v[34:37], v[74:77]
	s_nop 0
	v_mfma_f32_16x16x32_bf16 v[18:21], v[18:21], v[10:13], v[30:33]
	v_mfma_f32_16x16x32_bf16 v[126:129], v[22:25], v[38:41], v[74:77]
	s_nop 4
	v_mul_f32_e64 v76, v28, v132
	v_mul_f32_e64 v77, v29, v133
	v_pk_mul_f32 v[74:75], v[26:27], v[130:131]
	v_mfma_f32_16x16x32_bf16 v[122:125], v[22:25], v[14:17], v[18:21]
	s_nop 2
	v_mul_f32_e64 v20, v28, v136
	v_mul_f32_e64 v21, v29, v137
	v_pk_mul_f32 v[18:19], v[26:27], v[134:135]
	v_mfma_f32_16x16x32_bf16 v[34:37], v[2:5], v[34:37], v[74:77]
	s_nop 0
	v_mfma_f32_16x16x32_bf16 v[2:5], v[2:5], v[10:13], v[18:21]
	v_lshl_add_u64 v[10:11], v[164:165], 0, s[58:59]
	v_mfma_f32_16x16x32_bf16 v[130:133], v[6:9], v[38:41], v[34:37]
	v_mfma_f32_16x16x32_bf16 v[134:137], v[6:9], v[14:17], v[2:5]
	v_lshl_add_u64 v[6:7], v[160:161], 0, s[66:67]
	v_lshl_add_u64 v[14:15], v[142:143], 0, s[54:55]
	s_nop 2
	v_lshl_add_u64 v[2:3], v[140:141], 0, s[56:57]
	global_load_dwordx4 v[74:77], v[2:3], off
	global_load_dwordx4 v[78:81], v[2:3], off offset:1024
	global_load_dwordx4 v[82:85], v[2:3], off offset:2048
	global_load_dwordx4 v[86:89], v[2:3], off offset:3072
	global_load_dwordx4 v[18:21], v[6:7], off
	global_load_dwordx4 v[22:25], v[6:7], off offset:1024
	global_load_dwordx4 v[30:33], v[10:11], off
	s_nop 0
	global_load_dwordx4 v[2:5], v[6:7], off offset:2048
	s_nop 0
	global_load_dwordx4 v[6:9], v[6:7], off offset:3072
	s_nop 0
	global_load_dwordx4 v[26:29], v[10:11], off offset:64
	global_load_dwordx4 v[34:37], v[14:15], off
	global_load_dwordx4 v[38:41], v[14:15], off offset:1024
	s_nop 0
	global_load_dwordx4 v[10:13], v[14:15], off offset:2048
	s_nop 0
	global_load_dwordx4 v[14:17], v[14:15], off offset:3072
	s_nop 0
	global_load_dwordx4 v[114:117], v[114:115], off
	v_cvt_pk_bf16_f32 v214, v126, v127
	v_cvt_pk_bf16_f32 v215, v128, v129
	v_cvt_pk_bf16_f32 v216, v130, v131
	v_cvt_pk_bf16_f32 v217, v132, v133
	s_waitcnt vmcnt(30)
	v_mfma_f32_16x16x32_bf16 v[234:237], v[214:217], v[106:109], 0
	s_nop 7
	ds_write_b128 v139, v[234:237]
	s_waitcnt vmcnt(29)
	v_mfma_f32_16x16x32_bf16 v[234:237], v[214:217], v[102:105], 0
	s_nop 7
	ds_write_b128 v139, v[234:237] offset:1024
	s_waitcnt vmcnt(28)
	v_mfma_f32_16x16x32_bf16 v[234:237], v[214:217], v[98:101], 0
	s_waitcnt vmcnt(27)
	v_mfma_f32_16x16x32_bf16 v[214:217], v[214:217], v[110:113], 0
	s_nop 5
	ds_write_b128 v139, v[234:237] offset:2048
	s_nop 0
	ds_write_b128 v139, v[214:217] offset:3072
	v_cvt_pk_bf16_f32 v214, v122, v123
	v_cvt_pk_bf16_f32 v215, v124, v125
	v_cvt_pk_bf16_f32 v216, v134, v135
	v_cvt_pk_bf16_f32 v217, v136, v137
	s_nop 0
	v_mfma_f32_16x16x32_bf16 v[98:101], v[214:217], v[98:101], 0
	v_mfma_f32_16x16x32_bf16 v[106:109], v[214:217], v[106:109], 0
	v_mfma_f32_16x16x32_bf16 v[102:105], v[214:217], v[102:105], 0
	s_nop 5
	ds_write_b128 v139, v[98:101] offset:6144
	ds_write_b128 v139, v[106:109] offset:4096
	v_add_u32_e32 v106, s25, v212
	v_mfma_f32_16x16x32_bf16 v[98:101], v[214:217], v[110:113], 0
	ds_write_b128 v139, v[102:105] offset:5120
	s_nop 6
	ds_write_b128 v139, v[98:101] offset:7168
	s_waitcnt lgkmcnt(0)
	s_barrier
; __device__ __forceinline__ void phase_gla_seq(KArgs a, LAS unsigned char* lds, int tid, int wave, int lane) {
;     ...
;             G2B_LOAD(qA, kA, vA, dA, oA, 0);
;             __syncthreads();
;             for (int ch = 0; ch < NCHUNK; ch += 2) {
;                 G2B_LOAD(qB, kB, vB, dB, oB, ch + 1); asm volatile("" ::: "memory"); G2B_STEP(qA, kA, vA, dA, oA, ch);
;                 G2B_LOAD(qA, kA, vA, dA, oA, ch + 2); asm volatile("" ::: "memory"); G2B_STEP(qB, kB, vB, dB, oB, ch + 1);
;             }
;     ...
;             float* So = a->out + OUT_PS + (size_t)bh * 256 * 512 + l16;
; #pragma unroll
;             for (int vs = 0; vs < 2; ++vs)
; #pragma unroll
;                 for (int i = 0; i < 2; ++i)
; #pragma unroll
;                     for (int j = 0; j < 4; ++j) So[(size_t)((2 * wave + i) * 16 + 4 * g4 + j) * 512 + (vs32 * 2 + vs) * 16] = S[vs][i][j];
;             __syncthreads();
	ds_read_b128 v[98:101], v106
	ds_read_b128 v[238:241], v106 offset:8192
	ds_read_b128 v[242:245], v106 offset:16384
	ds_read_b128 v[246:249], v106 offset:24576
	ds_read_b128 v[250:253], v106 offset:32768
	s_waitcnt vmcnt(16) lgkmcnt(4)
	v_pk_add_f32 v[102:103], v[120:121], v[100:101]
	v_pk_add_f32 v[104:105], v[118:119], v[98:99]
	ds_read_b128 v[98:101], v106 offset:40960
	s_waitcnt lgkmcnt(4)
	v_pk_add_f32 v[102:103], v[102:103], v[240:241]
	v_pk_add_f32 v[104:105], v[104:105], v[238:239]
	ds_read_b128 v[238:241], v106 offset:49152
	s_waitcnt lgkmcnt(4)
	v_pk_add_f32 v[102:103], v[102:103], v[244:245]
	v_pk_add_f32 v[104:105], v[104:105], v[242:243]
	ds_read_b128 v[242:245], v106 offset:57344
	s_waitcnt lgkmcnt(4)
	v_pk_add_f32 v[102:103], v[102:103], v[248:249]
	v_pk_add_f32 v[104:105], v[104:105], v[246:247]
	s_waitcnt lgkmcnt(3)
	v_pk_add_f32 v[102:103], v[102:103], v[252:253]
	v_pk_add_f32 v[104:105], v[104:105], v[250:251]
	s_waitcnt lgkmcnt(2)
	v_pk_add_f32 v[102:103], v[102:103], v[100:101]
	v_pk_add_f32 v[104:105], v[104:105], v[98:99]
	s_waitcnt lgkmcnt(1)
	v_pk_add_f32 v[102:103], v[102:103], v[240:241]
	v_pk_add_f32 v[104:105], v[104:105], v[238:239]
	s_waitcnt lgkmcnt(0)
	v_pk_add_f32 v[100:101], v[102:103], v[244:245]
	v_or_b32_e32 v103, s21, v209
	v_or_b32_e32 v102, s20, v208
	v_lshlrev_b64 v[102:103], 13, v[102:103]
	v_pk_add_f32 v[98:99], v[104:105], v[242:243]
	v_lshl_add_u64 v[102:103], v[196:197], 0, v[102:103]
	global_store_dwordx4 v[102:103], v[98:101], off
	v_lshl_add_u64 v[208:209], v[208:209], 0, s[52:53]
	s_nop 0
	v_pk_mul_f32 v[100:101], v[72:73], v[128:129]
	v_pk_mul_f32 v[98:99], v[70:71], v[126:127]
	v_pk_mul_f32 v[72:73], v[72:73], v[124:125]
	v_pk_mul_f32 v[70:71], v[70:71], v[122:123]
	v_mfma_f32_16x16x32_bf16 v[98:101], v[42:45], v[90:93], v[98:101]
	s_nop 0
	v_mfma_f32_16x16x32_bf16 v[42:45], v[42:45], v[62:65], v[70:73]
	v_mfma_f32_16x16x32_bf16 v[126:129], v[46:49], v[94:97], v[98:101]
	s_nop 4
	v_mul_f32_e64 v100, v60, v132
	v_mul_f32_e64 v101, v61, v133
	v_pk_mul_f32 v[98:99], v[58:59], v[130:131]
	v_mfma_f32_16x16x32_bf16 v[122:125], v[46:49], v[66:69], v[42:45]
	s_nop 2
	v_mul_f32_e64 v44, v60, v136
	v_mul_f32_e64 v45, v61, v137
	v_pk_mul_f32 v[42:43], v[58:59], v[134:135]
	v_mfma_f32_16x16x32_bf16 v[90:93], v[50:53], v[90:93], v[98:101]
	s_nop 0
	v_mfma_f32_16x16x32_bf16 v[42:45], v[50:53], v[62:65], v[42:45]
	v_mfma_f32_16x16x32_bf16 v[130:133], v[54:57], v[94:97], v[90:93]
	v_mfma_f32_16x16x32_bf16 v[134:137], v[54:57], v[66:69], v[42:45]
	s_cbranch_scc0 .LBB0_893
	s_load_dwordx2 s[8:9], s[14:15], 0x110
	s_lshl_b64 s[18:19], s[18:19], 19
	v_mov_b32_e32 v195, v1
	s_waitcnt lgkmcnt(0)
	s_add_u32 s18, s8, s18
	s_addc_u32 s19, s9, s19
	s_lshl_b32 s48, s48, 6
	s_waitcnt vmcnt(8)
	v_lshl_add_u64 v[2:3], s[18:19], 0, v[194:195]
	v_lshl_add_u64 v[2:3], v[2:3], 0, s[48:49]
	s_mov_b64 s[18:19], 0x4120000
	v_lshl_add_u64 v[2:3], v[2:3], 0, s[18:19]
	v_readlane_b32 s18, v255, 2
	v_lshl_add_u64 v[4:5], v[2:3], 0, v[144:145]
	s_waitcnt vmcnt(7)
	v_lshl_add_u64 v[6:7], v[2:3], 0, v[146:147]
	v_lshl_add_u64 v[8:9], v[2:3], 0, v[148:149]
	s_waitcnt vmcnt(3)
	v_lshl_add_u64 v[10:11], v[2:3], 0, v[150:151]
	v_lshl_add_u64 v[12:13], v[2:3], 0, v[152:153]
	s_waitcnt vmcnt(2)
	v_lshl_add_u64 v[14:15], v[2:3], 0, v[154:155]
	v_lshl_add_u64 v[16:17], v[2:3], 0, v[156:157]
	v_lshl_add_u64 v[2:3], v[2:3], 0, v[158:159]
	v_readlane_b32 s19, v255, 3
	global_store_dword v[4:5], v126, off
	global_store_dword v[6:7], v127, off
	global_store_dword v[8:9], v128, off
	global_store_dword v[10:11], v129, off
	global_store_dword v[12:13], v130, off
	global_store_dword v[14:15], v131, off
	global_store_dword v[16:17], v132, off
	global_store_dword v[2:3], v133, off
	global_store_dword v[4:5], v122, off offset:64
	global_store_dword v[6:7], v123, off offset:64
	global_store_dword v[8:9], v124, off offset:64
	global_store_dword v[10:11], v125, off offset:64
	global_store_dword v[12:13], v134, off offset:64
	global_store_dword v[14:15], v135, off offset:64
	global_store_dword v[16:17], v136, off offset:64
	global_store_dword v[2:3], v137, off offset:64
	s_barrier
	s_load_dword s18, s[18:19], 0x10
	s_waitcnt lgkmcnt(0)
	s_lshr_b32 s18, s18, 16
	s_cmp_lg_u32 s18, 0
	s_cselect_b64 s[18:19], -1, 0
	s_cmp_lg_u64 s[18:19], 0
	s_addc_u32 s27, s27, s73
	s_cmpk_gt_i32 s27, 0xff
	s_cbranch_scc0 .LBB0_892
	v_readlane_b32 s67, v255, 4
	s_mov_b32 s35, 0x500000
	s_mov_b32 s66, 0x700000
	s_mov_b32 s37, 0x800000
	s_mov_b32 s56, 0xc00000
	s_mov_b32 s57, 0xe00000
